# NSA selected-branch fast path: QK reordered first-key-half first with a 4-deep K fragment ring; exp of the first half issued under the second half's QK MFMAs
# speedup vs baseline: 1.0142x; 1.0058x over previous
.LBB0_746:
	s_cmp_lt_i32 s92, 32
	s_cselect_b64 vcc, -1, 0
	s_cmp_lt_u32 s92, 64
	s_cselect_b64 s[72:73], -1, 0
	s_cmpk_lt_u32 s92, 0x60
	s_cselect_b64 s[76:77], -1, 0
	v_cndmask_b32_e64 v101, v147, v146, s[76:77]
	v_cndmask_b32_e64 v101, v101, v145, s[72:73]
	v_cndmask_b32_e32 v101, v101, v144, vcc
	s_and_b32 s76, s92, 31
	v_lshrrev_b32_e32 v225, s92, v101
	v_and_b32_e32 v225, 1, v225
	v_bfe_u32 v101, v101, s76, 1
	v_cmp_eq_u32_e64 s[72:73], 1, v225
	v_cmp_ne_u32_e32 vcc, 0, v101
	s_cbranch_vccz .LBB0_743
	s_lshl_b32 s76, s91, 14
	s_add_i32 s91, s76, 0
	s_cmp_eq_u32 s92, s33
	s_cbranch_scc0 .Lsel_fast2
	v_add_u32_e32 v0, s91, v184
	ds_read_b128 v[2:5], v0
	ds_read_b128 v[6:9], v0 offset:8192
	v_add_u32_e32 v0, s91, v185
	ds_read_b128 v[10:13], v0
	ds_read_b128 v[208:211], v0 offset:8192
	v_add_u32_e32 v0, s91, v186
	ds_read_b128 v[212:215], v0
	ds_read_b128 v[216:219], v0 offset:8192
	s_waitcnt lgkmcnt(0)
	v_mfma_f32_32x32x16_bf16 v[80:95], v[2:5], v[140:143], 0
	v_mfma_f32_32x32x16_bf16 v[96:111], v[6:9], v[140:143], 0
	v_add_u32_e32 v0, s91, v183
	ds_read_b128 v[2:5], v0
	ds_read_b128 v[6:9], v0 offset:8192
	v_mfma_f32_32x32x16_bf16 v[80:95], v[10:13], v[136:139], v[80:95]
	v_mfma_f32_32x32x16_bf16 v[96:111], v[208:211], v[136:139], v[96:111]
	v_add_u32_e32 v0, s91, v182
	ds_read_b128 v[10:13], v0
	ds_read_b128 v[208:211], v0 offset:8192
	v_mfma_f32_32x32x16_bf16 v[80:95], v[212:215], v[132:135], v[80:95]
	v_mfma_f32_32x32x16_bf16 v[96:111], v[216:219], v[132:135], v[96:111]
	v_add_u32_e32 v0, s91, v181
	ds_read_b128 v[212:215], v0
	ds_read_b128 v[216:219], v0 offset:8192
	s_waitcnt lgkmcnt(0)
	v_mfma_f32_32x32x16_bf16 v[80:95], v[2:5], v[128:131], v[80:95]
	v_mfma_f32_32x32x16_bf16 v[96:111], v[6:9], v[128:131], v[96:111]
	v_add_u32_e32 v0, s91, v180
	ds_read_b128 v[2:5], v0
	ds_read_b128 v[6:9], v0 offset:8192
	v_mfma_f32_32x32x16_bf16 v[80:95], v[10:13], v[124:127], v[80:95]
	v_mfma_f32_32x32x16_bf16 v[96:111], v[208:211], v[124:127], v[96:111]
	v_add_u32_e32 v0, s91, v179
	ds_read_b128 v[10:13], v0
	ds_read_b128 v[208:211], v0 offset:8192
	v_mfma_f32_32x32x16_bf16 v[80:95], v[212:215], v[120:123], v[80:95]
	v_mfma_f32_32x32x16_bf16 v[96:111], v[216:219], v[120:123], v[96:111]
	s_waitcnt lgkmcnt(0)
	v_mfma_f32_32x32x16_bf16 v[80:95], v[2:5], v[116:119], v[80:95]
	v_mfma_f32_32x32x16_bf16 v[96:111], v[6:9], v[116:119], v[96:111]
	v_mfma_f32_32x32x16_bf16 v[80:95], v[10:13], v[112:115], v[80:95]
	v_mfma_f32_32x32x16_bf16 v[96:111], v[208:211], v[112:115], v[96:111]
	s_nop 10
	s_cmp_eq_u32 s92, s33
	s_cbranch_scc0 .Lsel_fast
	v_exp_f32_e32 v6, v80
	v_exp_f32_e32 v0, v96
	v_exp_f32_e32 v9, v81
	v_exp_f32_e32 v3, v97
	v_exp_f32_e32 v8, v82
	v_exp_f32_e32 v2, v98
	v_exp_f32_e32 v11, v83
	v_exp_f32_e32 v5, v99
	v_exp_f32_e32 v10, v84
	v_exp_f32_e32 v4, v100
	v_exp_f32_e32 v13, v85
	v_exp_f32_e32 v7, v101
	v_exp_f32_e32 v96, v86
	v_exp_f32_e32 v82, v102
	v_exp_f32_e32 v97, v87
	v_exp_f32_e32 v83, v103
	v_exp_f32_e32 v88, v88
	v_exp_f32_e32 v14, v104
	v_exp_f32_e32 v89, v89
	v_exp_f32_e32 v15, v105
	v_exp_f32_e32 v90, v90
	v_exp_f32_e32 v80, v106
	v_exp_f32_e32 v91, v91
	v_exp_f32_e32 v81, v107
	v_exp_f32_e32 v92, v92
	v_exp_f32_e32 v84, v108
	v_exp_f32_e32 v93, v93
	v_exp_f32_e32 v85, v109
	v_exp_f32_e32 v94, v94
	v_exp_f32_e32 v86, v110
	v_exp_f32_e32 v95, v95
	v_exp_f32_e32 v87, v111
	s_cmp_eq_u32 s92, s33
	s_mov_b64 s[76:77], -1
	s_cbranch_scc1 .LBB0_749
	s_mov_b64 s[76:77], 0

.Lsel_fast2:
	v_add_u32_e32 v0, s91, v184
	ds_read_b128 v[2:5], v0
	v_add_u32_e32 v0, s91, v185
	ds_read_b128 v[208:211], v0
	v_add_u32_e32 v0, s91, v186
	ds_read_b128 v[212:215], v0
	v_add_u32_e32 v0, s91, v183
	ds_read_b128 v[216:219], v0
	s_waitcnt lgkmcnt(3)
	v_mfma_f32_32x32x16_bf16 v[80:95], v[2:5], v[140:143], 0
	v_add_u32_e32 v0, s91, v182
	ds_read_b128 v[2:5], v0
	s_waitcnt lgkmcnt(3)
	v_mfma_f32_32x32x16_bf16 v[80:95], v[208:211], v[136:139], v[80:95]
	v_add_u32_e32 v0, s91, v181
	ds_read_b128 v[208:211], v0
	s_waitcnt lgkmcnt(3)
	v_mfma_f32_32x32x16_bf16 v[80:95], v[212:215], v[132:135], v[80:95]
	v_add_u32_e32 v0, s91, v180
	ds_read_b128 v[212:215], v0
	s_waitcnt lgkmcnt(3)
	v_mfma_f32_32x32x16_bf16 v[80:95], v[216:219], v[128:131], v[80:95]
	v_add_u32_e32 v0, s91, v179
	ds_read_b128 v[216:219], v0
	s_waitcnt lgkmcnt(3)
	v_mfma_f32_32x32x16_bf16 v[80:95], v[2:5], v[124:127], v[80:95]
	v_add_u32_e32 v0, s91, v184
	ds_read_b128 v[2:5], v0 offset:8192
	s_waitcnt lgkmcnt(3)
	v_mfma_f32_32x32x16_bf16 v[80:95], v[208:211], v[120:123], v[80:95]
	v_add_u32_e32 v0, s91, v185
	ds_read_b128 v[208:211], v0 offset:8192
	s_waitcnt lgkmcnt(3)
	v_mfma_f32_32x32x16_bf16 v[80:95], v[212:215], v[116:119], v[80:95]
	v_add_u32_e32 v0, s91, v186
	ds_read_b128 v[212:215], v0 offset:8192
	s_waitcnt lgkmcnt(3)
	v_mfma_f32_32x32x16_bf16 v[80:95], v[216:219], v[112:115], v[80:95]
	v_add_u32_e32 v0, s91, v183
	ds_read_b128 v[216:219], v0 offset:8192
	s_waitcnt lgkmcnt(3)
	v_mfma_f32_32x32x16_bf16 v[96:111], v[2:5], v[140:143], 0
	v_add_u32_e32 v0, s91, v182
	ds_read_b128 v[2:5], v0 offset:8192
	s_waitcnt lgkmcnt(3)
	v_mfma_f32_32x32x16_bf16 v[96:111], v[208:211], v[136:139], v[96:111]
	v_add_u32_e32 v0, s91, v181
	ds_read_b128 v[208:211], v0 offset:8192
	s_waitcnt lgkmcnt(3)
	v_mfma_f32_32x32x16_bf16 v[96:111], v[212:215], v[132:135], v[96:111]
	v_add_u32_e32 v0, s91, v180
	ds_read_b128 v[212:215], v0 offset:8192
	s_waitcnt lgkmcnt(3)
	v_mfma_f32_32x32x16_bf16 v[96:111], v[216:219], v[128:131], v[96:111]
	v_add_u32_e32 v0, s91, v179
	ds_read_b128 v[216:219], v0 offset:8192
	v_exp_f32_e32 v80, v80
	v_exp_f32_e32 v81, v81
	v_exp_f32_e32 v82, v82
	s_waitcnt lgkmcnt(3)
	v_mfma_f32_32x32x16_bf16 v[96:111], v[2:5], v[124:127], v[96:111]
	v_exp_f32_e32 v83, v83
	v_exp_f32_e32 v84, v84
	v_exp_f32_e32 v85, v85
	s_waitcnt lgkmcnt(2)
	v_mfma_f32_32x32x16_bf16 v[96:111], v[208:211], v[120:123], v[96:111]
	v_exp_f32_e32 v86, v86
	v_exp_f32_e32 v87, v87
	v_exp_f32_e32 v88, v88
	s_waitcnt lgkmcnt(1)
	v_mfma_f32_32x32x16_bf16 v[96:111], v[212:215], v[116:119], v[96:111]
	v_exp_f32_e32 v89, v89
	v_exp_f32_e32 v90, v90
	v_exp_f32_e32 v91, v91
	s_waitcnt lgkmcnt(0)
	v_mfma_f32_32x32x16_bf16 v[96:111], v[216:219], v[112:115], v[96:111]
	v_exp_f32_e32 v92, v92
	v_exp_f32_e32 v93, v93
	v_exp_f32_e32 v94, v94
	v_exp_f32_e32 v95, v95
	v_add_u32_e32 v207, s91, v153
	v_add3_u32 v0, v207, v199, v178
	v_add_u32_e32 v6, s91, v200
	v_add3_u32 v6, v6, v178, v153
	v_add3_u32 v7, v207, v201, v178
	v_add_u32_e32 v230, s91, v202
	v_add3_u32 v230, v230, v178, v153
	ds_read_b64_tr_b16 v[12:13], v0 offset:32768
	ds_read_b64_tr_b16 v[14:15], v6 offset:34816
	ds_read_b64_tr_b16 v[208:209], v0 offset:36864
	ds_read_b64_tr_b16 v[210:211], v6 offset:38912
	ds_read_b64_tr_b16 v[212:213], v7 offset:32768
	ds_read_b64_tr_b16 v[214:215], v230 offset:34816
	ds_read_b64_tr_b16 v[216:217], v7 offset:36864
	ds_read_b64_tr_b16 v[218:219], v230 offset:38912
	v_add3_u32 v231, v207, v203, v178
	v_add_u32_e32 v241, s91, v204
	v_add3_u32 v241, v241, v178, v153
	v_add3_u32 v242, v207, v205, v178
	v_add_u32_e32 v243, s91, v206
	v_add3_u32 v243, v243, v178, v153
	s_nop 0
	v_pk_add_f32 v[244:245], v[80:81], v[82:83]
	v_pk_add_f32 v[246:247], v[84:85], v[86:87]
	v_pk_add_f32 v[232:233], v[88:89], v[90:91]
	v_pk_add_f32 v[234:235], v[92:93], v[94:95]
	v_pk_add_f32 v[244:245], v[244:245], v[246:247]
	v_pk_add_f32 v[232:233], v[232:233], v[234:235]
	v_pk_add_f32 v[244:245], v[244:245], v[232:233]
	v_add_f32_e32 v240, v244, v245
	v_cvt_pk_bf16_f32 v8, v80, v81
	v_cvt_pk_bf16_f32 v9, v82, v83
	v_cvt_pk_bf16_f32 v10, v84, v85
	v_cvt_pk_bf16_f32 v11, v86, v87
	v_cvt_pk_bf16_f32 v88, v88, v89
	v_cvt_pk_bf16_f32 v89, v90, v91
	v_cvt_pk_bf16_f32 v90, v92, v93
	v_cvt_pk_bf16_f32 v91, v94, v95
	v_cndmask_b32_e64 v8, 0, v8, s[72:73]
	v_cndmask_b32_e64 v9, 0, v9, s[72:73]
	v_cndmask_b32_e64 v10, 0, v10, s[72:73]
	v_cndmask_b32_e64 v11, 0, v11, s[72:73]
	v_cndmask_b32_e64 v88, 0, v88, s[72:73]
	v_cndmask_b32_e64 v89, 0, v89, s[72:73]
	v_cndmask_b32_e64 v90, 0, v90, s[72:73]
	v_cndmask_b32_e64 v91, 0, v91, s[72:73]
	ds_read_b64_tr_b16 v[80:81], v231 offset:32768
	ds_read_b64_tr_b16 v[82:83], v241 offset:34816
	ds_read_b64_tr_b16 v[84:85], v231 offset:36864
	ds_read_b64_tr_b16 v[86:87], v241 offset:38912
	ds_read_b64_tr_b16 v[92:93], v242 offset:32768
	ds_read_b64_tr_b16 v[94:95], v243 offset:34816
	ds_read_b64_tr_b16 v[236:237], v242 offset:36864
	ds_read_b64_tr_b16 v[238:239], v243 offset:38912
	s_waitcnt lgkmcnt(8)
	v_mfma_f32_32x32x16_bf16 v[64:79], v[8:11], v[12:15], v[64:79]
	v_exp_f32_e32 v96, v96
	v_exp_f32_e32 v97, v97
	v_mfma_f32_32x32x16_bf16 v[64:79], v[88:91], v[208:211], v[64:79]
	v_exp_f32_e32 v98, v98
	v_exp_f32_e32 v99, v99
	ds_read_b64_tr_b16 v[12:13], v0 offset:40960
	ds_read_b64_tr_b16 v[14:15], v6 offset:43008
	ds_read_b64_tr_b16 v[208:209], v0 offset:45056
	ds_read_b64_tr_b16 v[210:211], v6 offset:47104
	v_mfma_f32_32x32x16_bf16 v[48:63], v[8:11], v[212:215], v[48:63]
	v_exp_f32_e32 v100, v100
	v_exp_f32_e32 v101, v101
	v_mfma_f32_32x32x16_bf16 v[48:63], v[88:91], v[216:219], v[48:63]
	v_exp_f32_e32 v102, v102
	v_exp_f32_e32 v103, v103
	ds_read_b64_tr_b16 v[212:213], v7 offset:40960
	ds_read_b64_tr_b16 v[214:215], v230 offset:43008
	ds_read_b64_tr_b16 v[216:217], v7 offset:45056
	ds_read_b64_tr_b16 v[218:219], v230 offset:47104
	s_waitcnt lgkmcnt(8)
	v_mfma_f32_32x32x16_bf16 v[32:47], v[8:11], v[80:83], v[32:47]
	v_exp_f32_e32 v104, v104
	v_exp_f32_e32 v105, v105
	v_mfma_f32_32x32x16_bf16 v[32:47], v[88:91], v[84:87], v[32:47]
	v_exp_f32_e32 v106, v106
	v_exp_f32_e32 v107, v107
	ds_read_b64_tr_b16 v[80:81], v231 offset:40960
	ds_read_b64_tr_b16 v[82:83], v241 offset:43008
	ds_read_b64_tr_b16 v[84:85], v231 offset:45056
	ds_read_b64_tr_b16 v[86:87], v241 offset:47104
	v_mfma_f32_32x32x16_bf16 v[16:31], v[8:11], v[92:95], v[16:31]
	v_exp_f32_e32 v108, v108
	v_exp_f32_e32 v109, v109
	v_mfma_f32_32x32x16_bf16 v[16:31], v[88:91], v[236:239], v[16:31]
	v_exp_f32_e32 v110, v110
	v_exp_f32_e32 v111, v111
	ds_read_b64_tr_b16 v[92:93], v242 offset:40960
	ds_read_b64_tr_b16 v[94:95], v243 offset:43008
	ds_read_b64_tr_b16 v[236:237], v242 offset:45056
	ds_read_b64_tr_b16 v[238:239], v243 offset:47104
	v_pk_add_f32 v[244:245], v[96:97], v[98:99]
	v_pk_add_f32 v[246:247], v[100:101], v[102:103]
	v_pk_add_f32 v[6:7], v[104:105], v[106:107]
	v_pk_add_f32 v[230:231], v[108:109], v[110:111]
	v_pk_add_f32 v[244:245], v[244:245], v[246:247]
	v_pk_add_f32 v[6:7], v[6:7], v[230:231]
	v_pk_add_f32 v[244:245], v[244:245], v[6:7]
	v_add_f32_e32 v244, v244, v245
	v_cvt_pk_bf16_f32 v2, v96, v97
	v_cvt_pk_bf16_f32 v3, v98, v99
	v_cvt_pk_bf16_f32 v4, v100, v101
	v_cvt_pk_bf16_f32 v5, v102, v103
	v_cvt_pk_bf16_f32 v232, v104, v105
	v_cvt_pk_bf16_f32 v233, v106, v107
	v_cvt_pk_bf16_f32 v234, v108, v109
	v_cvt_pk_bf16_f32 v235, v110, v111
	v_cndmask_b32_e64 v2, 0, v2, s[72:73]
	v_cndmask_b32_e64 v3, 0, v3, s[72:73]
	v_cndmask_b32_e64 v4, 0, v4, s[72:73]
	v_cndmask_b32_e64 v5, 0, v5, s[72:73]
	v_cndmask_b32_e64 v232, 0, v232, s[72:73]
	v_cndmask_b32_e64 v233, 0, v233, s[72:73]
	v_cndmask_b32_e64 v234, 0, v234, s[72:73]
	v_cndmask_b32_e64 v235, 0, v235, s[72:73]
	v_add_f32_e32 v240, v240, v244
	v_cndmask_b32_e64 v240, 0, v240, s[72:73]
	v_add_f32_e32 v198, v198, v240
	s_waitcnt lgkmcnt(12)
	v_mfma_f32_32x32x16_bf16 v[64:79], v[2:5], v[12:15], v[64:79]
	v_mfma_f32_32x32x16_bf16 v[64:79], v[232:235], v[208:211], v[64:79]
	s_waitcnt lgkmcnt(8)
	v_mfma_f32_32x32x16_bf16 v[48:63], v[2:5], v[212:215], v[48:63]
	v_mfma_f32_32x32x16_bf16 v[48:63], v[232:235], v[216:219], v[48:63]
	s_waitcnt lgkmcnt(4)
	v_mfma_f32_32x32x16_bf16 v[32:47], v[2:5], v[80:83], v[32:47]
	v_mfma_f32_32x32x16_bf16 v[32:47], v[232:235], v[84:87], v[32:47]
	s_waitcnt lgkmcnt(0)
	v_mfma_f32_32x32x16_bf16 v[16:31], v[2:5], v[92:95], v[16:31]
	v_mfma_f32_32x32x16_bf16 v[16:31], v[232:235], v[236:239], v[16:31]
	s_branch .LBB0_743
